# w_in indexer-k / head-weight tile fast path with wave-uniform skips (s_cbranch_execz) so waves without columns issue no masked stores
# baseline (speedup 1.0000x reference)
.Lwin_ki:
	s_cmp_gt_u32 s14, 255
	s_cbranch_scc1 .Lwin_slow
	s_mov_b64 s[98:99], exec
	v_cmp_gt_u32_e32 vcc, 64, v146
	s_and_b64 exec, s[98:99], vcc
	s_cbranch_execz .Lwin_ki_w
	s_add_u32 s60, s22, 0x36e00000
	s_addc_u32 s61, s23, 0
	s_add_u32 s100, s20, 0x18200000
	s_addc_u32 s101, s21, 0
	s_lshl_b32 s56, s14, 15
	s_add_u32 s60, s60, s56
	s_addc_u32 s61, s61, 0
	s_lshl_b32 s56, s14, 16
	s_add_u32 s100, s100, s56
	s_addc_u32 s101, s101, 0
	v_lshlrev_b32_e32 v174, 7, v149
	v_lshl_add_u32 v174, v146, 1, v174
	v_lshlrev_b32_e32 v175, 8, v149
	v_lshl_add_u32 v175, v146, 2, v175
	global_store_dwordx4 v175, v[124:127], s[100:101]
	global_store_dwordx4 v175, v[120:123], s[100:101] offset:16
	v_cvt_pk_bf16_f32 v128, v124, v125
	v_cvt_pk_bf16_f32 v129, v126, v127
	v_cvt_pk_bf16_f32 v130, v120, v121
	v_cvt_pk_bf16_f32 v131, v122, v123
	global_store_dwordx4 v174, v[128:131], s[60:61]
	s_add_u32 s60, s60, 0x800
	s_addc_u32 s61, s61, 0
	s_add_u32 s100, s100, 0x1000
	s_addc_u32 s101, s101, 0
	global_store_dwordx4 v175, v[108:111], s[100:101]
	global_store_dwordx4 v175, v[104:107], s[100:101] offset:16
	v_cvt_pk_bf16_f32 v132, v108, v109
	v_cvt_pk_bf16_f32 v133, v110, v111
	v_cvt_pk_bf16_f32 v134, v104, v105
	v_cvt_pk_bf16_f32 v135, v106, v107
	global_store_dwordx4 v174, v[132:135], s[60:61]
	s_add_u32 s60, s60, 0x800
	s_addc_u32 s61, s61, 0
	s_add_u32 s100, s100, 0x1000
	s_addc_u32 s101, s101, 0
	global_store_dwordx4 v175, v[92:95], s[100:101]
	global_store_dwordx4 v175, v[88:91], s[100:101] offset:16
	v_cvt_pk_bf16_f32 v128, v92, v93
	v_cvt_pk_bf16_f32 v129, v94, v95
	v_cvt_pk_bf16_f32 v130, v88, v89
	v_cvt_pk_bf16_f32 v131, v90, v91
	global_store_dwordx4 v174, v[128:131], s[60:61]
	s_add_u32 s60, s60, 0x800
	s_addc_u32 s61, s61, 0
	s_add_u32 s100, s100, 0x1000
	s_addc_u32 s101, s101, 0
	global_store_dwordx4 v175, v[76:79], s[100:101]
	global_store_dwordx4 v175, v[72:75], s[100:101] offset:16
	v_cvt_pk_bf16_f32 v132, v76, v77
	v_cvt_pk_bf16_f32 v133, v78, v79
	v_cvt_pk_bf16_f32 v134, v72, v73
	v_cvt_pk_bf16_f32 v135, v74, v75
	global_store_dwordx4 v174, v[132:135], s[60:61]
	s_add_u32 s60, s60, 0x2800
	s_addc_u32 s61, s61, 0
	s_add_u32 s100, s100, 0x5000
	s_addc_u32 s101, s101, 0
	global_store_dwordx4 v175, v[60:63], s[100:101]
	global_store_dwordx4 v175, v[56:59], s[100:101] offset:16
	v_cvt_pk_bf16_f32 v128, v60, v61
	v_cvt_pk_bf16_f32 v129, v62, v63
	v_cvt_pk_bf16_f32 v130, v56, v57
	v_cvt_pk_bf16_f32 v131, v58, v59
	global_store_dwordx4 v174, v[128:131], s[60:61]
	s_add_u32 s60, s60, 0x800
	s_addc_u32 s61, s61, 0
	s_add_u32 s100, s100, 0x1000
	s_addc_u32 s101, s101, 0
	global_store_dwordx4 v175, v[44:47], s[100:101]
	global_store_dwordx4 v175, v[40:43], s[100:101] offset:16
	v_cvt_pk_bf16_f32 v132, v44, v45
	v_cvt_pk_bf16_f32 v133, v46, v47
	v_cvt_pk_bf16_f32 v134, v40, v41
	v_cvt_pk_bf16_f32 v135, v42, v43
	global_store_dwordx4 v174, v[132:135], s[60:61]
	s_add_u32 s60, s60, 0x800
	s_addc_u32 s61, s61, 0
	s_add_u32 s100, s100, 0x1000
	s_addc_u32 s101, s101, 0
	global_store_dwordx4 v175, v[28:31], s[100:101]
	global_store_dwordx4 v175, v[24:27], s[100:101] offset:16
	v_cvt_pk_bf16_f32 v128, v28, v29
	v_cvt_pk_bf16_f32 v129, v30, v31
	v_cvt_pk_bf16_f32 v130, v24, v25
	v_cvt_pk_bf16_f32 v131, v26, v27
	global_store_dwordx4 v174, v[128:131], s[60:61]
	s_add_u32 s60, s60, 0x800
	s_addc_u32 s61, s61, 0
	s_add_u32 s100, s100, 0x1000
	s_addc_u32 s101, s101, 0
	global_store_dwordx4 v175, v[12:15], s[100:101]
	global_store_dwordx4 v175, v[8:11], s[100:101] offset:16
	v_cvt_pk_bf16_f32 v132, v12, v13
	v_cvt_pk_bf16_f32 v133, v14, v15
	v_cvt_pk_bf16_f32 v134, v8, v9
	v_cvt_pk_bf16_f32 v135, v10, v11
	global_store_dwordx4 v174, v[132:135], s[60:61]
.Lwin_ki_w:
	s_mov_b64 exec, s[98:99]
	v_cmp_eq_u32_e32 vcc, 64, v146
	s_and_b64 exec, s[98:99], vcc
	s_cbranch_execz .Lwin_ki_e
	s_add_u32 s100, s22, 0x37600000
	s_addc_u32 s101, s23, 0
	s_lshl_b32 s56, s14, 13
	s_add_u32 s100, s100, s56
	s_addc_u32 s101, s101, 0
	v_lshlrev_b32_e32 v175, 5, v149
	global_store_dwordx4 v175, v[124:127], s[100:101]
	global_store_dwordx4 v175, v[120:123], s[100:101] offset:16
	s_add_u32 s100, s100, 0x200
	s_addc_u32 s101, s101, 0
	global_store_dwordx4 v175, v[108:111], s[100:101]
	global_store_dwordx4 v175, v[104:107], s[100:101] offset:16
	s_add_u32 s100, s100, 0x200
	s_addc_u32 s101, s101, 0
	global_store_dwordx4 v175, v[92:95], s[100:101]
	global_store_dwordx4 v175, v[88:91], s[100:101] offset:16
	s_add_u32 s100, s100, 0x200
	s_addc_u32 s101, s101, 0
	global_store_dwordx4 v175, v[76:79], s[100:101]
	global_store_dwordx4 v175, v[72:75], s[100:101] offset:16
	s_add_u32 s100, s100, 0xa00
	s_addc_u32 s101, s101, 0
	global_store_dwordx4 v175, v[60:63], s[100:101]
	global_store_dwordx4 v175, v[56:59], s[100:101] offset:16
	s_add_u32 s100, s100, 0x200
	s_addc_u32 s101, s101, 0
	global_store_dwordx4 v175, v[44:47], s[100:101]
	global_store_dwordx4 v175, v[40:43], s[100:101] offset:16
	s_add_u32 s100, s100, 0x200
	s_addc_u32 s101, s101, 0
	global_store_dwordx4 v175, v[28:31], s[100:101]
	global_store_dwordx4 v175, v[24:27], s[100:101] offset:16
	s_add_u32 s100, s100, 0x200
	s_addc_u32 s101, s101, 0
	global_store_dwordx4 v175, v[12:15], s[100:101]
	global_store_dwordx4 v175, v[8:11], s[100:101] offset:16
.Lwin_ki_e:
	s_mov_b64 exec, s[98:99]
	s_branch .Lwin_done
